# DIFF attention loop LDS reads batched; attention queue atomic prefetched one unit ahead; FOX epilogue no longer drains stores before the unit-end barrier
# speedup vs baseline: 1.0142x; 1.0064x over previous
.LBB0_833:
	s_or_b64 exec, exec, s[4:5]
	s_waitcnt lgkmcnt(0)
	s_barrier
	v_mbcnt_lo_u32_b32 v6, -1, 0
	v_mbcnt_hi_u32_b32 v6, -1, v6
	s_getreg_b32 s2, hwreg(HW_REG_HW_ID, 0, 6)
	s_lshl_b32 s2, s2, 2
	s_and_b32 s2, s2, 0xfc
	s_add_i32 s2, s2, 0
	s_add_i32 s2, s2, 0x23400
	v_mov_b32_e32 v0, s2
	ds_read_b32 v7, v0
	s_load_dwordx16 s[16:31], s[84:85], 0x68
	s_load_dwordx4 s[40:43], s[84:85], 0xa8
	v_readlane_b32 s8, v255, 17
	s_load_dwordx2 s[4:5], s[84:85], 0x110
	v_readlane_b32 s6, v255, 31
	v_and_or_b32 v0, v6, 63, s8
	v_lshlrev_b64 v[2:3], 2, v[0:1]
	s_waitcnt lgkmcnt(0)
	v_lshl_add_u64 v[4:5], s[20:21], 0, v[2:3]
	global_load_dword v0, v[4:5], off
	v_lshl_add_u64 v[4:5], s[22:23], 0, v[2:3]
	global_load_dword v8, v[4:5], off
	v_lshl_add_u64 v[4:5], s[24:25], 0, v[2:3]
	global_load_dword v9, v[4:5], off
	v_lshl_add_u64 v[4:5], s[26:27], 0, v[2:3]
	global_load_dword v10, v[4:5], off
	v_lshl_add_u64 v[4:5], s[16:17], 0, v[2:3]
	global_load_dword v11, v[4:5], off
	v_lshl_add_u64 v[4:5], s[18:19], 0, v[2:3]
	global_load_dword v12, v[4:5], off
	v_lshl_add_u64 v[4:5], s[30:31], 0, v[2:3]
	global_load_dword v4, v[4:5], off
	v_lshl_add_u64 v[2:3], s[40:41], 0, v[2:3]
	global_load_dword v2, v[2:3], off
	v_readfirstlane_b32 s2, v7
	s_lshl_b32 s2, s2, 6
	s_add_u32 s94, s4, 0x11d00000
	s_addc_u32 s95, s5, 0
	s_add_u32 s96, s4, 0x15d00000
	s_addc_u32 s97, s5, 0
	s_add_u32 s56, s4, 0x19d00000
	s_addc_u32 s57, s5, 0
	s_add_u32 s77, s4, 0x600000
	s_addc_u32 s52, s5, 0
	v_readlane_b32 s7, v255, 32
	s_add_u32 s58, s28, s6
	s_addc_u32 s59, s29, s7
	v_readlane_b32 s6, v255, 19
	s_mov_b32 s3, s6
	s_mov_b32 s6, 0x3fb8aa3b
	s_cmp_eq_u32 s3, 0
	s_cselect_b64 vcc, -1, 0
	s_mov_b32 s3, 0x42b17218
	v_readlane_b32 s9, v255, 18
	v_readlane_b32 s7, v255, 20
	s_mov_b32 s65, s72
	s_waitcnt vmcnt(6)
	v_mul_f32_e32 v3, v0, v8
	ds_swizzle_b32 v3, v3 offset:swizzle(SWAP,1)
	s_waitcnt vmcnt(4)
	v_mul_f32_e32 v5, v9, v10
	ds_swizzle_b32 v5, v5 offset:swizzle(SWAP,1)
	s_waitcnt vmcnt(3)
	v_and_b32_e32 v7, 0x7fffffff, v11
	ds_swizzle_b32 v7, v7 offset:swizzle(SWAP,1)
	v_max_f32_e64 v11, |v11|, |v11|
	s_waitcnt lgkmcnt(2)
	v_fmac_f32_e32 v3, v0, v8
	s_waitcnt vmcnt(1)
	v_and_b32_e32 v14, 0x7fffffff, v4
	ds_swizzle_b32 v14, v14 offset:swizzle(SWAP,1)
	s_waitcnt lgkmcnt(1)
	v_max_f32_e32 v0, v7, v7
	v_max_f32_e64 v4, |v4|, |v4|
	v_max_f32_e32 v0, v11, v0
	v_fmac_f32_e32 v5, v9, v10
	s_waitcnt lgkmcnt(0)
	v_max_f32_e32 v8, v14, v14
	v_max_f32_e32 v4, v4, v8
	ds_swizzle_b32 v8, v0 offset:swizzle(SWAP,2)
	ds_swizzle_b32 v10, v3 offset:swizzle(SWAP,2)
	v_and_b32_e32 v13, 0x7fffffff, v12
	s_waitcnt vmcnt(0)
	v_and_b32_e32 v15, 0x7fffffff, v2
	ds_swizzle_b32 v13, v13 offset:swizzle(SWAP,1)
	s_waitcnt lgkmcnt(2)
	v_max_f32_e32 v8, v8, v8
	v_max_f32_e32 v0, v0, v8
	ds_swizzle_b32 v8, v0 offset:swizzle(SWAP,4)
	ds_swizzle_b32 v15, v15 offset:swizzle(SWAP,1)
	s_waitcnt lgkmcnt(3)
	v_add_f32_e32 v3, v3, v10
	ds_swizzle_b32 v10, v3 offset:swizzle(SWAP,4)
	v_max_f32_e64 v12, |v12|, |v12|
	s_waitcnt lgkmcnt(2)
	v_max_f32_e32 v8, v8, v8
	v_max_f32_e32 v0, v0, v8
	ds_swizzle_b32 v8, v0 offset:swizzle(SWAP,8)
	v_max_f32_e32 v7, v13, v13
	v_max_f32_e64 v2, |v2|, |v2|
	s_waitcnt lgkmcnt(2)
	v_max_f32_e32 v9, v15, v15
	v_max_f32_e32 v7, v12, v7
	s_waitcnt lgkmcnt(0)
	v_max_f32_e32 v8, v8, v8
	v_max_f32_e32 v0, v0, v8
	ds_swizzle_b32 v8, v0 offset:swizzle(SWAP,16)
	v_max_f32_e32 v2, v2, v9
	ds_swizzle_b32 v9, v7 offset:swizzle(SWAP,2)
	v_add_f32_e32 v3, v3, v10
	ds_swizzle_b32 v10, v3 offset:swizzle(SWAP,8)
	s_waitcnt lgkmcnt(2)
	v_max_f32_e32 v8, v8, v8
	v_max_f32_e32 v0, v0, v8
	v_mov_b32_e32 v8, v0
	s_nop 1
	v_permlane32_swap_b32_e32 v0, v8
	ds_swizzle_b32 v11, v4 offset:swizzle(SWAP,2)
	s_waitcnt lgkmcnt(2)
	v_max_f32_e32 v9, v9, v9
	v_max_f32_e32 v8, v8, v8
	v_max_f32_e32 v0, v0, v0
	v_max_f32_e32 v7, v7, v9
	v_max_f32_e32 v0, v0, v8
	ds_swizzle_b32 v8, v2 offset:swizzle(SWAP,2)
	ds_swizzle_b32 v9, v7 offset:swizzle(SWAP,4)
	s_waitcnt lgkmcnt(3)
	v_add_f32_e32 v3, v3, v10
	ds_swizzle_b32 v10, v3 offset:swizzle(SWAP,16)
	s_waitcnt lgkmcnt(3)
	v_max_f32_e32 v11, v11, v11
	v_max_f32_e32 v4, v4, v11
	s_waitcnt lgkmcnt(2)
	v_max_f32_e32 v8, v8, v8
	ds_swizzle_b32 v11, v4 offset:swizzle(SWAP,4)
	s_waitcnt lgkmcnt(2)
	v_max_f32_e32 v9, v9, v9
	v_max_f32_e32 v2, v2, v8
	v_max_f32_e32 v7, v7, v9
	ds_swizzle_b32 v8, v2 offset:swizzle(SWAP,4)
	ds_swizzle_b32 v9, v7 offset:swizzle(SWAP,8)
	s_waitcnt lgkmcnt(3)
	v_add_f32_e32 v3, v3, v10
	v_mov_b32_e32 v10, v3
	s_nop 1
	v_permlane32_swap_b32_e32 v3, v10
	v_add_f32_e32 v3, v3, v10
	s_waitcnt lgkmcnt(2)
	v_max_f32_e32 v10, v11, v11
	v_max_f32_e32 v4, v4, v10
	s_waitcnt lgkmcnt(1)
	v_max_f32_e32 v8, v8, v8
	s_waitcnt lgkmcnt(0)
	v_max_f32_e32 v9, v9, v9
	ds_swizzle_b32 v10, v4 offset:swizzle(SWAP,8)
	v_max_f32_e32 v2, v2, v8
	ds_swizzle_b32 v13, v5 offset:swizzle(SWAP,2)
	v_max_f32_e32 v7, v7, v9
	ds_swizzle_b32 v8, v2 offset:swizzle(SWAP,8)
	ds_swizzle_b32 v9, v7 offset:swizzle(SWAP,16)
	s_waitcnt lgkmcnt(3)
	v_max_f32_e32 v10, v10, v10
	s_waitcnt lgkmcnt(2)
	v_add_f32_e32 v5, v5, v13
	v_max_f32_e32 v4, v4, v10
	s_waitcnt lgkmcnt(1)
	v_max_f32_e32 v8, v8, v8
	ds_swizzle_b32 v12, v5 offset:swizzle(SWAP,4)
	s_waitcnt lgkmcnt(1)
	v_max_f32_e32 v9, v9, v9
	ds_swizzle_b32 v10, v4 offset:swizzle(SWAP,16)
	v_max_f32_e32 v2, v2, v8
	v_max_f32_e32 v7, v7, v9
	ds_swizzle_b32 v8, v2 offset:swizzle(SWAP,16)
	v_mov_b32_e32 v9, v7
	s_nop 1
	v_permlane32_swap_b32_e32 v7, v9
	v_max_f32_e32 v9, v9, v9
	v_max_f32_e32 v7, v7, v7
	s_waitcnt lgkmcnt(2)
	v_add_f32_e32 v5, v5, v12
	v_max_f32_e32 v7, v7, v9
	s_waitcnt lgkmcnt(1)
	v_max_f32_e32 v9, v10, v10
	ds_swizzle_b32 v12, v5 offset:swizzle(SWAP,8)
	v_max_f32_e32 v4, v4, v9
	s_waitcnt lgkmcnt(1)
	v_max_f32_e32 v8, v8, v8
	v_mov_b32_e32 v9, v4
	v_max_f32_e32 v2, v2, v8
	s_nop 0
	v_permlane32_swap_b32_e32 v4, v9
	v_mov_b32_e32 v8, v2
	v_max_f32_e32 v9, v9, v9
	v_max_f32_e32 v4, v4, v4
	v_permlane32_swap_b32_e32 v2, v8
	v_mul_f32_e32 v0, 0x413c5bb7, v0
	v_max_f32_e32 v4, v4, v9
	v_max_f32_e32 v8, v8, v8
	v_max_f32_e32 v2, v2, v2
	v_mul_f32_e32 v0, v0, v7
	s_waitcnt lgkmcnt(0)
	v_add_f32_e32 v5, v5, v12
	v_max_f32_e32 v2, v2, v8
	v_readfirstlane_b32 s80, v0
	v_mul_f32_e32 v0, 0x413c5bb7, v4
	ds_swizzle_b32 v12, v5 offset:swizzle(SWAP,16)
	v_mul_f32_e32 v0, v0, v2
	v_mov_b32_e32 v7, 0x3e4ccccd
	v_readfirstlane_b32 s81, v0
	v_mul_f32_e32 v0, 0x3fb8aa3b, v3
	v_fma_f32 v2, v3, s6, -v0
	v_rndne_f32_e32 v4, v0
	v_fmac_f32_e32 v2, 0x32a5705f, v3
	v_sub_f32_e32 v0, v0, v4
	v_add_f32_e32 v0, v0, v2
	s_waitcnt lgkmcnt(0)
	v_add_f32_e32 v5, v5, v12
	v_exp_f32_e32 v0, v0
	v_cvt_i32_f32_e32 v2, v4
	v_mov_b32_e32 v12, v5
	s_nop 1
	v_permlane32_swap_b32_e32 v5, v12
	v_add_f32_e32 v5, v5, v12
	v_mov_b32_e32 v4, 0x3ef1014c
	v_ldexp_f32 v0, v0, v2
	v_mul_f32_e32 v2, 0x3fb8aa3b, v5
	v_cndmask_b32_e32 v4, v4, v7, vcc
	v_fma_f32 v7, v5, s6, -v2
	v_rndne_f32_e32 v8, v2
	v_fmac_f32_e32 v7, 0x32a5705f, v5
	v_sub_f32_e32 v2, v2, v8
	v_add_f32_e32 v2, v2, v7
	v_exp_f32_e32 v2, v2
	v_cvt_i32_f32_e32 v7, v8
	v_cmp_ngt_f32_e32 vcc, s82, v3
	s_lshl_b64 s[6:7], s[8:9], 2
	v_sub_f32_e32 v134, 1.0, v4
	v_cndmask_b32_e32 v0, 0, v0, vcc
	v_cmp_nlt_f32_e32 vcc, s3, v3
	v_ldexp_f32 v2, v2, v7
	s_nop 0
	v_cndmask_b32_e32 v0, v229, v0, vcc
	v_cmp_ngt_f32_e32 vcc, s82, v5
	s_add_u32 s82, s4, s6
	s_addc_u32 s83, s5, s7
	v_cndmask_b32_e32 v2, 0, v2, vcc
	v_cmp_nlt_f32_e32 vcc, s3, v5
	s_nop 1
	v_cndmask_b32_e32 v2, v229, v2, vcc
	v_sub_f32_e32 v0, v0, v2
	v_add_f32_e32 v0, v0, v4
	s_nop 0
	v_readfirstlane_b32 s12, v0
	v_sub_u32_e32 v0, 0, v6
	v_cmp_eq_u32_e64 s[4:5], s2, v0
	s_mov_b32 s13, s12
	s_mov_b32 s100, 0
	s_mov_b32 s101, 0
	s_branch .LBB0_837
.LBB0_834:
	s_lshl_b64 s[6:7], s[74:75], 11
	s_add_u32 s2, s94, s6
	s_nop 1
	v_rcp_f32_e32 v4, v62
	s_addc_u32 s6, s95, s7
	s_add_u32 s2, s2, s3
	s_addc_u32 s3, s6, 0
	v_lshlrev_b32_e32 v0, 1, v136
	v_lshl_add_u64 v[2:3], s[2:3], 0, v[0:1]
	v_lshlrev_b32_e32 v0, 13, v135
	v_rcp_f32_e32 v5, v63
	v_lshl_add_u64 v[2:3], v[2:3], 0, v[0:1]
	v_mul_f32_e32 v0, v32, v4
	v_cvt_pk_bf16_f32 v0, v0, s0
	global_store_short v[2:3], v0, off offset:1024
	v_mul_f32_e32 v0, v16, v4
	v_cvt_pk_bf16_f32 v0, v0, s0
	v_rcp_f32_e32 v6, v64
	global_store_short v[2:3], v0, off offset:1088
	v_mul_f32_e32 v0, v33, v5
	v_cvt_pk_bf16_f32 v0, v0, s0
	global_store_short v[2:3], v0, off offset:3072
	v_mul_f32_e32 v0, v17, v5
	v_cvt_pk_bf16_f32 v0, v0, s0
	s_movk_i32 s2, 0x1000
	v_rcp_f32_e32 v7, v65
	global_store_short v[2:3], v0, off offset:3136
	v_mul_f32_e32 v0, v34, v6
	v_add_co_u32_e32 v4, vcc, s2, v2
	v_cvt_pk_bf16_f32 v0, v0, s0
	s_nop 0
	v_addc_co_u32_e32 v5, vcc, 0, v3, vcc
	global_store_short v[4:5], v0, off offset:1024
	v_mul_f32_e32 v0, v18, v6
	v_cvt_pk_bf16_f32 v0, v0, s0
	v_rcp_f32_e32 v8, v66
	global_store_short v[4:5], v0, off offset:1088
	v_mul_f32_e32 v0, v35, v7
	v_cvt_pk_bf16_f32 v0, v0, s0
	global_store_short v[4:5], v0, off offset:3072
	v_mul_f32_e32 v0, v19, v7
	v_cvt_pk_bf16_f32 v0, v0, s0
	s_movk_i32 s2, 0x4000
	v_rcp_f32_e32 v9, v67
	global_store_short v[4:5], v0, off offset:3136
	v_mul_f32_e32 v0, v36, v8
	v_add_co_u32_e32 v4, vcc, s2, v2
	v_cvt_pk_bf16_f32 v0, v0, s0
	s_nop 0
	v_addc_co_u32_e32 v5, vcc, 0, v3, vcc
	global_store_short v[4:5], v0, off offset:1024
	v_mul_f32_e32 v0, v20, v8
	v_cvt_pk_bf16_f32 v0, v0, s0
	v_rcp_f32_e32 v10, v68
	global_store_short v[4:5], v0, off offset:1088
	v_mul_f32_e32 v0, v37, v9
	v_cvt_pk_bf16_f32 v0, v0, s0
	global_store_short v[4:5], v0, off offset:3072
	v_mul_f32_e32 v0, v21, v9
	v_cvt_pk_bf16_f32 v0, v0, s0
	s_movk_i32 s2, 0x5000
	v_rcp_f32_e32 v11, v69
	global_store_short v[4:5], v0, off offset:3136
	v_mul_f32_e32 v0, v38, v10
	v_add_co_u32_e32 v4, vcc, s2, v2
	v_cvt_pk_bf16_f32 v0, v0, s0
	s_nop 0
	v_addc_co_u32_e32 v5, vcc, 0, v3, vcc
	global_store_short v[4:5], v0, off offset:1024
	v_mul_f32_e32 v0, v22, v10
	v_cvt_pk_bf16_f32 v0, v0, s0
	v_rcp_f32_e32 v12, v70
	global_store_short v[4:5], v0, off offset:1088
	v_mul_f32_e32 v0, v39, v11
	v_cvt_pk_bf16_f32 v0, v0, s0
	global_store_short v[4:5], v0, off offset:3072
	v_mul_f32_e32 v0, v23, v11
	v_cvt_pk_bf16_f32 v0, v0, s0
	s_mov_b32 s2, 0x8000
	v_rcp_f32_e32 v13, v71
	global_store_short v[4:5], v0, off offset:3136
	v_mul_f32_e32 v0, v40, v12
	v_add_co_u32_e32 v4, vcc, s2, v2
	v_cvt_pk_bf16_f32 v0, v0, s0
	s_nop 0
	v_addc_co_u32_e32 v5, vcc, 0, v3, vcc
	global_store_short v[4:5], v0, off offset:1024
	v_mul_f32_e32 v0, v24, v12
	v_cvt_pk_bf16_f32 v0, v0, s0
	v_rcp_f32_e32 v14, v72
	global_store_short v[4:5], v0, off offset:1088
	v_mul_f32_e32 v0, v41, v13
	v_cvt_pk_bf16_f32 v0, v0, s0
	global_store_short v[4:5], v0, off offset:3072
	v_mul_f32_e32 v0, v25, v13
	v_cvt_pk_bf16_f32 v0, v0, s0
	s_mov_b32 s2, 0x9000
	v_rcp_f32_e32 v15, v73
	global_store_short v[4:5], v0, off offset:3136
	v_mul_f32_e32 v0, v42, v14
	v_add_co_u32_e32 v4, vcc, s2, v2
	v_cvt_pk_bf16_f32 v0, v0, s0
	s_nop 0
	v_addc_co_u32_e32 v5, vcc, 0, v3, vcc
	global_store_short v[4:5], v0, off offset:1024
	v_mul_f32_e32 v0, v26, v14
	v_cvt_pk_bf16_f32 v0, v0, s0
	v_rcp_f32_e32 v48, v74
	global_store_short v[4:5], v0, off offset:1088
	v_mul_f32_e32 v0, v43, v15
	v_cvt_pk_bf16_f32 v0, v0, s0
	global_store_short v[4:5], v0, off offset:3072
	v_mul_f32_e32 v0, v27, v15
	v_cvt_pk_bf16_f32 v0, v0, s0
	s_mov_b32 s2, 0xc000
	v_rcp_f32_e32 v49, v75
	global_store_short v[4:5], v0, off offset:3136
	v_mul_f32_e32 v0, v44, v48
	v_add_co_u32_e32 v4, vcc, s2, v2
	v_cvt_pk_bf16_f32 v0, v0, s0
	s_nop 0
	v_addc_co_u32_e32 v5, vcc, 0, v3, vcc
	global_store_short v[4:5], v0, off offset:1024
	v_mul_f32_e32 v0, v28, v48
	v_cvt_pk_bf16_f32 v0, v0, s0
	v_rcp_f32_e32 v50, v76
	global_store_short v[4:5], v0, off offset:1088
	v_mul_f32_e32 v0, v45, v49
	v_cvt_pk_bf16_f32 v0, v0, s0
	global_store_short v[4:5], v0, off offset:3072
	v_mul_f32_e32 v0, v29, v49
	v_cvt_pk_bf16_f32 v0, v0, s0
	s_mov_b32 s2, 0xd000
	v_rcp_f32_e32 v51, v77
	global_store_short v[4:5], v0, off offset:3136
	v_mul_f32_e32 v0, v46, v50
	v_add_co_u32_e32 v2, vcc, s2, v2
	v_cvt_pk_bf16_f32 v0, v0, s0
	s_nop 0
	v_addc_co_u32_e32 v3, vcc, 0, v3, vcc
	global_store_short v[2:3], v0, off offset:1024
	v_mul_f32_e32 v0, v30, v50
	v_cvt_pk_bf16_f32 v0, v0, s0
	global_store_short v[2:3], v0, off offset:1088
	v_mul_f32_e32 v0, v47, v51
	v_cvt_pk_bf16_f32 v0, v0, s0
	global_store_short v[2:3], v0, off offset:3072
	v_mul_f32_e32 v0, v31, v51
	v_cvt_pk_bf16_f32 v0, v0, s0
	global_store_short v[2:3], v0, off offset:3136
	s_waitcnt lgkmcnt(0)
	s_barrier

.LBB0_837:
	s_and_saveexec_b64 s[6:7], s[4:5]
	s_cbranch_execz .Lq_pub_done
	s_cmp_eq_u32 s101, 0
	s_cbranch_scc1 .Lq_try
	s_waitcnt vmcnt(32)
	v_readfirstlane_b32 s3, v222
	s_and_b32 s2, s101, 0xff
	s_mov_b32 s101, 0
	s_cmp_lt_u32 s3, 0x100
	s_cbranch_scc1 .Lq_got
	s_add_i32 s100, s100, 1
	s_cmp_lt_u32 s100, 8
	s_cbranch_scc1 .Lq_try
	s_branch .Lq_none

.Lq_none:
	s_movk_i32 s3, 0x7fff
	s_mov_b32 s2, 0
.Lq_got:
	s_lshl_b32 s2, s2, 8
	s_or_b32 s2, s2, s3
	v_mov_b32_e32 v0, s2
	v_mov_b32_e32 v2, s49
	ds_write_b32 v2, v0
	s_cmp_lt_u32 s3, 0x100
	s_cbranch_scc0 .Lq_pub_done
	s_getreg_b32 s2, hwreg(HW_REG_XCC_ID, 0, 4)
	s_add_i32 s2, s2, s100
	s_and_b32 s2, s2, 7
	s_or_b32 s101, s2, 0x100
	s_lshl_b32 s3, s2, 9
	s_add_i32 s3, s3, 0x300
	v_mov_b32_e32 v3, s3
	v_mov_b32_e32 v222, 1
	global_atomic_add v222, v3, v222, s[82:83] offset:256 sc0

.LBB0_856:
	s_lshl_b32 s6, s7, 15
	s_add_i32 s64, s6, 0
	s_add_i32 s6, s64, s92
	v_add3_u32 v253, s6, v136, v137
	v_add_u32_e32 v252, s64, v138
	ds_read_b128 v[186:189], v253
	ds_read_b128 v[190:193], v253 offset:512
	ds_read_b128 v[194:197], v253 offset:2048
	ds_read_b128 v[198:201], v253 offset:2560
	v_add3_u32 v252, v252, v132, v139
	ds_read_b128 v[202:205], v253 offset:4096
	ds_read_b128 v[206:209], v253 offset:4608
	ds_read_b128 v[210:213], v253 offset:6144
	ds_read_b128 v[214:217], v253 offset:6656
	ds_read_b64_tr_b16 v[236:237], v252 offset:16384
	ds_read_b64_tr_b16 v[238:239], v252 offset:16896
	ds_read_b64_tr_b16 v[240:241], v252 offset:17408
	ds_read_b64_tr_b16 v[242:243], v252 offset:17920
	ds_read_b64_tr_b16 v[244:245], v252 offset:18432
	ds_read_b64_tr_b16 v[246:247], v252 offset:18944
	ds_read_b64_tr_b16 v[248:249], v252 offset:19456
	s_waitcnt lgkmcnt(14)
	v_mfma_f32_32x32x16_bf16 v[82:97], v[186:189], v[114:117], v[66:81]
	s_waitcnt lgkmcnt(13)
	v_mfma_f32_32x32x16_bf16 v[98:113], v[190:193], v[114:117], v[66:81]
	ds_read_b64_tr_b16 v[250:251], v252 offset:19968
	s_waitcnt lgkmcnt(13)
	v_mfma_f32_32x32x16_bf16 v[82:97], v[194:197], v[118:121], v[82:97]
	s_waitcnt lgkmcnt(12)
	v_mfma_f32_32x32x16_bf16 v[98:113], v[198:201], v[118:121], v[98:113]
	s_waitcnt lgkmcnt(11)
	v_mfma_f32_32x32x16_bf16 v[82:97], v[202:205], v[122:125], v[82:97]
	s_waitcnt lgkmcnt(10)
	v_mfma_f32_32x32x16_bf16 v[98:113], v[206:209], v[122:125], v[98:113]
	s_waitcnt lgkmcnt(9)
	v_mfma_f32_32x32x16_bf16 v[82:97], v[210:213], v[126:129], v[82:97]
	s_waitcnt lgkmcnt(8)
	v_mfma_f32_32x32x16_bf16 v[98:113], v[214:217], v[126:129], v[98:113]
	ds_read_b64_tr_b16 v[186:187], v252 offset:20480
	ds_read_b64_tr_b16 v[188:189], v252 offset:20992
	ds_read_b64_tr_b16 v[190:191], v252 offset:21504
	ds_read_b64_tr_b16 v[192:193], v252 offset:22016
	ds_read_b64_tr_b16 v[194:195], v252 offset:22528
	ds_read_b64_tr_b16 v[196:197], v252 offset:23040
	ds_read_b64_tr_b16 v[198:199], v252 offset:23552
	ds_read_b64_tr_b16 v[200:201], v252 offset:24064
	ds_read_b64_tr_b16 v[202:203], v252 offset:24576
	ds_read_b64_tr_b16 v[204:205], v252 offset:25088
	ds_read_b64_tr_b16 v[206:207], v252 offset:25600
	ds_read_b64_tr_b16 v[208:209], v252 offset:26112
	ds_read_b64_tr_b16 v[210:211], v252 offset:26624
	ds_read_b64_tr_b16 v[212:213], v252 offset:27136
	ds_read_b64_tr_b16 v[214:215], v252 offset:27648
	ds_read_b64_tr_b16 v[216:217], v252 offset:28160
	v_add_u32_e32 v0, 59, v140
	s_add_i32 s6, s50, 0xb0
	s_cmp_le_i32 s6, s53
	s_cbranch_scc1 .LBB0_858
	v_add_u32_e32 v144, 58, v140
	v_med3_i32 v144, v144, 0, v234
	v_lshl_add_u32 v145, v144, 2, s73
	v_add_u32_e32 v144, 57, v140
	v_med3_i32 v144, v144, 0, v234
	v_add_u32_e32 v152, 42, v140
	v_lshl_add_u32 v146, v144, 2, s73
	v_add_u32_e32 v144, 56, v140
	v_med3_i32 v152, v152, 0, v234
	v_med3_i32 v144, v144, 0, v234
	v_lshl_add_u32 v153, v152, 2, s73
	v_add_u32_e32 v152, 41, v140
	v_lshl_add_u32 v147, v144, 2, s73
	v_add_u32_e32 v144, 51, v140
	v_med3_i32 v152, v152, 0, v234
	v_add_u32_e32 v160, 26, v140
	v_med3_i32 v144, v144, 0, v234
	v_lshl_add_u32 v154, v152, 2, s73
	v_add_u32_e32 v152, 40, v140
	v_med3_i32 v160, v160, 0, v234
	v_lshl_add_u32 v148, v144, 2, s73
	v_add_u32_e32 v144, 50, v140
	v_med3_i32 v152, v152, 0, v234
	v_lshl_add_u32 v161, v160, 2, s73
	v_add_u32_e32 v160, 25, v140
	v_med3_i32 v144, v144, 0, v234
	v_lshl_add_u32 v155, v152, 2, s73
	v_add_u32_e32 v152, 35, v140
	v_med3_i32 v160, v160, 0, v234
	v_lshl_add_u32 v149, v144, 2, s73
	v_add_u32_e32 v144, 49, v140
	v_med3_i32 v152, v152, 0, v234
	v_lshl_add_u32 v162, v160, 2, s73
	v_add_u32_e32 v160, 24, v140
	v_add_u32_e32 v168, 10, v140
	v_med3_i32 v144, v144, 0, v234
	v_lshl_add_u32 v156, v152, 2, s73
	v_add_u32_e32 v152, 34, v140
	v_med3_i32 v160, v160, 0, v234
	v_med3_i32 v168, v168, 0, v234
	v_lshl_add_u32 v150, v144, 2, s73
	v_add_u32_e32 v144, 48, v140
	v_med3_i32 v152, v152, 0, v234
	v_lshl_add_u32 v163, v160, 2, s73
	v_add_u32_e32 v160, 19, v140
	v_lshl_add_u32 v169, v168, 2, s73
	v_add_u32_e32 v168, 9, v140
	v_med3_i32 v143, v0, 0, v234
	v_med3_i32 v144, v144, 0, v234
	v_lshl_add_u32 v157, v152, 2, s73
	v_add_u32_e32 v152, 33, v140
	v_med3_i32 v160, v160, 0, v234
	v_med3_i32 v168, v168, 0, v234
	v_lshl_add_u32 v143, v143, 2, s73
	v_lshl_add_u32 v151, v144, 2, s73
	v_med3_i32 v152, v152, 0, v234
	v_lshl_add_u32 v164, v160, 2, s73
	v_add_u32_e32 v160, 18, v140
	v_lshl_add_u32 v180, v168, 2, s73
	v_add_u32_e32 v168, 8, v140
	ds_read_b32 v144, v143
	ds_read_b32 v145, v145
	ds_read_b32 v146, v146
	ds_read_b32 v147, v147
	ds_read_b32 v148, v148
	ds_read_b32 v149, v149
	ds_read_b32 v150, v150
	ds_read_b32 v151, v151
	v_add_u32_e32 v143, 43, v140
	v_lshl_add_u32 v158, v152, 2, s73
	v_add_u32_e32 v152, 32, v140
	v_med3_i32 v160, v160, 0, v234
	v_med3_i32 v168, v168, 0, v234
	v_med3_i32 v143, v143, 0, v234
	v_med3_i32 v152, v152, 0, v234
	v_lshl_add_u32 v165, v160, 2, s73
	v_add_u32_e32 v160, 17, v140
	v_lshl_add_u32 v181, v168, 2, s73
	v_add_u32_e32 v168, 3, v140
	v_lshl_add_u32 v143, v143, 2, s73
	v_lshl_add_u32 v159, v152, 2, s73
	v_med3_i32 v160, v160, 0, v234
	v_med3_i32 v168, v168, 0, v234
	ds_read_b32 v152, v143
	ds_read_b32 v153, v153
	ds_read_b32 v154, v154
	ds_read_b32 v155, v155
	ds_read_b32 v156, v156
	ds_read_b32 v157, v157
	ds_read_b32 v158, v158
	ds_read_b32 v159, v159
	v_add_u32_e32 v143, 27, v140
	v_lshl_add_u32 v166, v160, 2, s73
	v_add_u32_e32 v160, 16, v140
	v_lshl_add_u32 v182, v168, 2, s73
	v_add_u32_e32 v168, 2, v140
	v_med3_i32 v143, v143, 0, v234
	v_med3_i32 v160, v160, 0, v234
	v_med3_i32 v168, v168, 0, v234
	v_lshl_add_u32 v143, v143, 2, s73
	v_lshl_add_u32 v167, v160, 2, s73
	v_lshl_add_u32 v183, v168, 2, s73
	v_add_u32_e32 v168, 1, v140
	ds_read_b32 v160, v143
	ds_read_b32 v161, v161
	ds_read_b32 v162, v162
	ds_read_b32 v163, v163
	ds_read_b32 v164, v164
	ds_read_b32 v165, v165
	ds_read_b32 v166, v166
	ds_read_b32 v167, v167
	v_add_u32_e32 v143, 11, v140
	v_med3_i32 v168, v168, 0, v234
	v_med3_i32 v143, v143, 0, v234
	v_lshl_add_u32 v184, v168, 2, s73
	v_med3_i32 v168, v140, 0, v234
	v_lshl_add_u32 v143, v143, 2, s73
	v_lshl_add_u32 v185, v168, 2, s73
	ds_read_b32 v168, v143
	ds_read_b32 v169, v169
	ds_read_b32 v180, v180
	ds_read_b32 v181, v181
	ds_read_b32 v182, v182
	ds_read_b32 v183, v183
	ds_read_b32 v184, v184
	ds_read_b32 v185, v185
	s_waitcnt lgkmcnt(0)
	v_pk_add_f32 v[96:97], v[96:97], v[158:159]
	v_pk_add_f32 v[94:95], v[94:95], v[156:157]
	v_pk_add_f32 v[92:93], v[92:93], v[154:155]
	v_pk_add_f32 v[90:91], v[90:91], v[152:153]
	v_pk_add_f32 v[88:89], v[88:89], v[150:151]
	v_pk_add_f32 v[86:87], v[86:87], v[148:149]
	v_pk_add_f32 v[84:85], v[84:85], v[146:147]
	v_pk_add_f32 v[82:83], v[82:83], v[144:145]
	v_pk_add_f32 v[112:113], v[112:113], v[184:185]
	v_pk_add_f32 v[110:111], v[110:111], v[182:183]
	v_pk_add_f32 v[108:109], v[108:109], v[180:181]
	v_pk_add_f32 v[106:107], v[106:107], v[168:169]
	v_pk_add_f32 v[104:105], v[104:105], v[166:167]
	v_pk_add_f32 v[102:103], v[102:103], v[164:165]
	v_pk_add_f32 v[100:101], v[100:101], v[162:163]
	v_pk_add_f32 v[98:99], v[98:99], v[160:161]

.LBB0_860:
	s_nop 0
	v_exp_f32_e32 v82, v82
	s_nop 0
	v_exp_f32_e32 v98, v98
	v_exp_f32_e32 v83, v83
	v_exp_f32_e32 v99, v99
	v_exp_f32_e32 v84, v84
	v_exp_f32_e32 v100, v100
	v_exp_f32_e32 v85, v85
	v_exp_f32_e32 v101, v101
	v_exp_f32_e32 v86, v86
	v_exp_f32_e32 v102, v102
	v_exp_f32_e32 v87, v87
	v_exp_f32_e32 v103, v103
	v_exp_f32_e32 v88, v88
	v_exp_f32_e32 v104, v104
	v_exp_f32_e32 v89, v89
	v_exp_f32_e32 v105, v105
	v_exp_f32_e32 v90, v90
	v_exp_f32_e32 v106, v106
	v_exp_f32_e32 v91, v91
	v_exp_f32_e32 v107, v107
	v_exp_f32_e32 v92, v92
	v_exp_f32_e32 v108, v108
	v_exp_f32_e32 v93, v93
	v_exp_f32_e32 v109, v109
	v_exp_f32_e32 v144, v94
	v_exp_f32_e32 v110, v110
	v_exp_f32_e32 v145, v95
	v_exp_f32_e32 v111, v111
	v_exp_f32_e32 v146, v96
	v_exp_f32_e32 v112, v112
	v_exp_f32_e32 v147, v97
	v_exp_f32_e32 v113, v113
	v_pk_add_f32 v[156:157], v[84:85], v[100:101]
	v_pk_add_f32 v[158:159], v[82:83], v[98:99]
	v_pk_add_f32 v[152:153], v[88:89], v[104:105]
	v_pk_add_f32 v[154:155], v[86:87], v[102:103]
	v_pk_mov_b32 v[160:161], v[158:159], v[156:157] op_sel:[1,0]
	v_mov_b32_e32 v159, v157
	v_pk_add_f32 v[156:157], v[160:161], v[158:159]
	v_pk_mov_b32 v[158:159], v[154:155], v[152:153] op_sel:[1,0]
	v_mov_b32_e32 v155, v153
	v_pk_add_f32 v[152:153], v[158:159], v[154:155]
	v_pk_add_f32 v[94:95], v[146:147], v[112:113]
	v_pk_add_f32 v[96:97], v[144:145], v[110:111]
	v_pk_add_f32 v[148:149], v[92:93], v[108:109]
	v_pk_add_f32 v[150:151], v[90:91], v[106:107]
	v_pk_add_f32 v[156:157], v[156:157], v[156:157] op_sel_hi:[0,1]
	v_pk_add_f32 v[152:153], v[152:153], v[152:153] op_sel_hi:[0,1]
	v_add_f32_e32 v151, v150, v151
	v_add_f32_e32 v149, v148, v149
	v_mov_b32_e32 v150, v96
	v_mov_b32_e32 v148, v97
	v_mov_b32_e32 v156, v94
	v_mov_b32_e32 v152, v95
	v_pk_add_f32 v[96:97], v[150:151], v[148:149]
	v_pk_add_f32 v[94:95], v[156:157], v[152:153]
	v_cvt_pk_bf16_f32 v90, v90, v91
	v_pk_add_f32 v[94:95], v[96:97], v[94:95]
	v_cvt_pk_bf16_f32 v96, v86, v87
	v_cvt_pk_bf16_f32 v86, v98, v99
	v_cvt_pk_bf16_f32 v97, v88, v89
	v_cvt_pk_bf16_f32 v88, v102, v103
	v_add_f32_e32 v0, v94, v95
	v_cvt_pk_bf16_f32 v94, v82, v83
	v_cvt_pk_bf16_f32 v95, v84, v85
	v_cvt_pk_bf16_f32 v87, v100, v101
	v_cvt_pk_bf16_f32 v91, v92, v93
	v_cvt_pk_bf16_f32 v92, v144, v145
	v_cvt_pk_bf16_f32 v93, v146, v147
	v_cvt_pk_bf16_f32 v89, v104, v105
	v_cvt_pk_bf16_f32 v82, v106, v107
	v_cvt_pk_bf16_f32 v83, v108, v109
	v_cvt_pk_bf16_f32 v84, v110, v111
	v_cvt_pk_bf16_f32 v85, v112, v113
	v_add_f32_e32 v135, v135, v0
	s_waitcnt lgkmcnt(0)
	v_mfma_f32_32x32x16_bf16 v[50:65], v[94:97], v[236:239], v[50:65]
	v_mfma_f32_32x32x16_bf16 v[50:65], v[90:93], v[240:243], v[50:65]
	v_mfma_f32_32x32x16_bf16 v[50:65], v[86:89], v[244:247], v[50:65]
	v_mfma_f32_32x32x16_bf16 v[50:65], v[82:85], v[248:251], v[50:65]
	ds_read_b64_tr_b16 v[236:237], v252 offset:28672
	ds_read_b64_tr_b16 v[238:239], v252 offset:29184
	ds_read_b64_tr_b16 v[240:241], v252 offset:29696
	ds_read_b64_tr_b16 v[242:243], v252 offset:30208
	ds_read_b64_tr_b16 v[244:245], v252 offset:30720
	ds_read_b64_tr_b16 v[246:247], v252 offset:31232
	ds_read_b64_tr_b16 v[248:249], v252 offset:31744
	ds_read_b64_tr_b16 v[250:251], v252 offset:32256
	v_mfma_f32_32x32x16_bf16 v[34:49], v[94:97], v[186:189], v[34:49]
	v_mfma_f32_32x32x16_bf16 v[34:49], v[90:93], v[190:193], v[34:49]
	v_mfma_f32_32x32x16_bf16 v[34:49], v[86:89], v[194:197], v[34:49]
	v_mfma_f32_32x32x16_bf16 v[34:49], v[82:85], v[198:201], v[34:49]
	v_mfma_f32_32x32x16_bf16 v[18:33], v[94:97], v[202:205], v[18:33]
	v_mfma_f32_32x32x16_bf16 v[18:33], v[90:93], v[206:209], v[18:33]
	v_mfma_f32_32x32x16_bf16 v[18:33], v[86:89], v[210:213], v[18:33]
	v_mfma_f32_32x32x16_bf16 v[18:33], v[82:85], v[214:217], v[18:33]
	s_waitcnt lgkmcnt(0)
	v_mfma_f32_32x32x16_bf16 v[2:17], v[94:97], v[236:239], v[2:17]
	v_mfma_f32_32x32x16_bf16 v[2:17], v[90:93], v[240:243], v[2:17]
	v_mfma_f32_32x32x16_bf16 v[2:17], v[86:89], v[244:247], v[2:17]
	v_mfma_f32_32x32x16_bf16 v[2:17], v[82:85], v[248:251], v[2:17]
	s_add_i32 s50, s50, 64
	s_cmp_eq_u32 s93, s3
	v_subrev_u32_e32 v140, 64, v140
	s_cbranch_scc1 .LBB0_865
